# attention loop: second QK block with 4-deep pipelined K-fragment reads in free VGPRs and finish-softmax VALU interleaved into its MFMA gaps; first-half probability block (fmamk/exp) hoisted into the P
# speedup vs baseline: 1.0175x; 1.0037x over previous
.LBB0_217:
	v_mfma_f32_32x32x16_bf16 v[32:47], v[100:103], v[112:115], v[32:47]
	v_max_f32_e32 v252, v85, v85
	v_max_f32_e32 v253, v84, v84
	v_max_f32_e32 v252, v253, v252
	v_max3_f32 v252, v252, v86, v87
	v_max3_f32 v252, v252, v88, v89
	ds_read_b64_tr_b16 v[112:113], v211 offset:0x200
	ds_read_b64_tr_b16 v[114:115], v211 offset:0xa00
	v_mfma_f32_32x32x16_bf16 v[32:47], v[64:67], v[116:119], v[32:47]
	v_max3_f32 v252, v252, v90, v91
	v_max3_f32 v252, v252, v92, v93
	v_max3_f32 v252, v252, v94, v95
	v_max3_f32 v252, v252, v96, v97
	v_max3_f32 v252, v252, v98, v99
	ds_read_b64_tr_b16 v[116:117], v211 offset:0x1200
	ds_read_b64_tr_b16 v[118:119], v211 offset:0x1a00
	v_mfma_f32_32x32x16_bf16 v[32:47], v[104:107], v[120:123], v[32:47]
	v_max3_f32 v252, v252, v68, v69
	v_max3_f32 v252, v252, v70, v71
	v_max3_f32 v252, v252, v72, v73
	v_max3_f32 v252, v252, v74, v75
	v_max3_f32 v252, v252, v76, v77
	ds_read_b64_tr_b16 v[120:121], v211 offset:0x2200
	ds_read_b64_tr_b16 v[122:123], v211 offset:0x2a00
	ds_read_b64_tr_b16 v[178:179], v211 offset:0x3200
	ds_read_b64_tr_b16 v[180:181], v211 offset:0x3a00
	s_waitcnt lgkmcnt(0)
	v_mfma_f32_32x32x16_bf16 v[32:47], v[108:111], v[124:127], v[32:47]
	v_max3_f32 v252, v252, v78, v79
	v_max3_f32 v252, v252, v80, v81
	v_max3_f32 v252, v252, v82, v83
	v_mov_b32_e32 v253, v252
	s_nop 1
	v_mfma_f32_32x32x16_bf16 v[48:63], v[100:103], v[112:115], v[48:63]
	v_permlane32_swap_b32_e32 v252, v253
	v_max_f32_e32 v253, v253, v253
	v_max_f32_e32 v252, v252, v252
	v_max_f32_e32 v252, v252, v253
	v_max_f32_e32 v255, v176, v176
	ds_read_b64_tr_b16 v[112:113], v211 offset:0x400
	ds_read_b64_tr_b16 v[114:115], v211 offset:0xc00
	v_mfma_f32_32x32x16_bf16 v[48:63], v[64:67], v[116:119], v[48:63]
	v_sub_f32_e32 v253, v252, v176
	v_max_f32_e32 v252, v255, v252
	v_sub_f32_e32 v255, v176, v252
	v_mul_f32_e32 v255, 0x3e0293ee, v255
	v_mul_f32_e32 v253, 0x3db504f3, v253
	ds_read_b64_tr_b16 v[116:117], v211 offset:0x1400
	ds_read_b64_tr_b16 v[118:119], v211 offset:0x1c00
	v_mfma_f32_32x32x16_bf16 v[48:63], v[104:107], v[120:123], v[48:63]
	v_exp_f32_e32 v255, v255
	v_cmp_ge_f32_e32 vcc, s82, v253
	s_cmp_eq_u64 vcc, exec
	s_cselect_b64 s[4:5], -1, 0
	ds_read_b64_tr_b16 v[120:121], v211 offset:0x2400
	ds_read_b64_tr_b16 v[122:123], v211 offset:0x2c00
	ds_read_b64_tr_b16 v[124:125], v211 offset:0x3400
	ds_read_b64_tr_b16 v[126:127], v211 offset:0x3c00
	s_waitcnt lgkmcnt(0)
	v_mfma_f32_32x32x16_bf16 v[48:63], v[108:111], v[178:181], v[48:63]
	v_cndmask_b32_e64 v227, v252, v176, s[4:5]
	v_mul_f32_e32 v176, 0xbe0293ee, v227
	v_fmamk_f32 v232, v84, 0x3e0293ee, v176
	v_fmamk_f32 v233, v85, 0x3e0293ee, v176
	v_fmamk_f32 v234, v86, 0x3e0293ee, v176
	v_fmamk_f32 v235, v87, 0x3e0293ee, v176
	v_mfma_f32_32x32x16_bf16 v[16:31], v[100:103], v[112:115], v[16:31]
	v_fmamk_f32 v236, v88, 0x3e0293ee, v176
	v_fmamk_f32 v237, v89, 0x3e0293ee, v176
	v_fmamk_f32 v238, v90, 0x3e0293ee, v176
	v_fmamk_f32 v239, v91, 0x3e0293ee, v176
	v_fmamk_f32 v240, v92, 0x3e0293ee, v176
	v_fmamk_f32 v241, v93, 0x3e0293ee, v176
	ds_read_b64_tr_b16 v[112:113], v211 offset:0x600
	ds_read_b64_tr_b16 v[114:115], v211 offset:0xe00
	v_mfma_f32_32x32x16_bf16 v[16:31], v[64:67], v[116:119], v[16:31]
	v_fmamk_f32 v242, v94, 0x3e0293ee, v176
	v_fmamk_f32 v243, v95, 0x3e0293ee, v176
	v_fmamk_f32 v96, v96, 0x3e0293ee, v176
	v_fmamk_f32 v97, v97, 0x3e0293ee, v176
	v_fmamk_f32 v98, v98, 0x3e0293ee, v176
	v_fmamk_f32 v99, v99, 0x3e0293ee, v176
	ds_read_b64_tr_b16 v[116:117], v211 offset:0x1600
	ds_read_b64_tr_b16 v[118:119], v211 offset:0x1e00
	v_mfma_f32_32x32x16_bf16 v[16:31], v[104:107], v[120:123], v[16:31]
	v_fmamk_f32 v84, v68, 0x3e0293ee, v176
	v_fmamk_f32 v93, v69, 0x3e0293ee, v176
	v_fmamk_f32 v94, v70, 0x3e0293ee, v176
	v_fmamk_f32 v95, v71, 0x3e0293ee, v176
	v_fmamk_f32 v177, v72, 0x3e0293ee, v176
	v_fmamk_f32 v85, v73, 0x3e0293ee, v176
	ds_read_b64_tr_b16 v[120:121], v211 offset:0x2600
	ds_read_b64_tr_b16 v[122:123], v211 offset:0x2e00
	ds_read_b64_tr_b16 v[178:179], v211 offset:0x3600
	ds_read_b64_tr_b16 v[180:181], v211 offset:0x3e00
	s_waitcnt lgkmcnt(0)
	v_mfma_f32_32x32x16_bf16 v[16:31], v[108:111], v[124:127], v[16:31]
	v_fmamk_f32 v86, v74, 0x3e0293ee, v176
	v_fmamk_f32 v87, v75, 0x3e0293ee, v176
	v_fmamk_f32 v88, v76, 0x3e0293ee, v176
	v_fmamk_f32 v89, v77, 0x3e0293ee, v176
	v_fmamk_f32 v90, v78, 0x3e0293ee, v176
	v_fmamk_f32 v91, v79, 0x3e0293ee, v176
	v_mfma_f32_32x32x16_bf16 v[0:15], v[100:103], v[112:115], v[0:15]
	v_exp_f32_e32 v68, v236
	v_exp_f32_e32 v69, v237
	v_exp_f32_e32 v70, v238
	v_exp_f32_e32 v71, v239
	v_exp_f32_e32 v72, v240
	v_exp_f32_e32 v73, v241
	v_mfma_f32_32x32x16_bf16 v[0:15], v[64:67], v[116:119], v[0:15]
	v_exp_f32_e32 v74, v242
	v_exp_f32_e32 v75, v243
	v_exp_f32_e32 v76, v96
	v_exp_f32_e32 v77, v97
	v_exp_f32_e32 v78, v98
	v_exp_f32_e32 v79, v99
	v_exp_f32_e32 v64, v232
	v_exp_f32_e32 v65, v233
	v_exp_f32_e32 v66, v234
	v_exp_f32_e32 v67, v235
	v_mfma_f32_32x32x16_bf16 v[0:15], v[104:107], v[120:123], v[0:15]
	v_fmamk_f32 v92, v80, 0x3e0293ee, v176
	v_mfma_f32_32x32x16_bf16 v[0:15], v[108:111], v[178:181], v[0:15]
	v_fmamk_f32 v178, v81, 0x3e0293ee, v176
	v_fmamk_f32 v179, v82, 0x3e0293ee, v176
	v_fmac_f32_e32 v176, 0x3e0293ee, v83
	s_barrier
	s_waitcnt vmcnt(0)
	v_cndmask_b32_e64 v225, v255, 1.0, s[4:5]
	v_cmp_gt_f32_e32 vcc, 1.0, v225
	s_waitcnt vmcnt(3)
	ds_write_b128 v199, v[160:163]
	s_waitcnt vmcnt(2)
	ds_write_b128 v216, v[164:167]
	s_waitcnt vmcnt(1)
	ds_write_b128 v213, v[168:171] offset:32768
	s_waitcnt vmcnt(0)
	ds_write_b128 v213, v[172:175] offset:40960
	s_cbranch_vccz .LBB0_221
	s_and_saveexec_b64 s[72:73], s[0:1]
	ds_write_b32 v214, v225 offset:128
	s_or_b64 exec, exec, s[72:73]
	s_waitcnt lgkmcnt(0)
	ds_read_b128 v[100:103], v212 offset:224
	ds_read_b128 v[104:107], v212 offset:192
	ds_read_b128 v[108:111], v212 offset:160
	ds_read_b128 v[112:115], v212 offset:128
	s_waitcnt lgkmcnt(3)
	v_pk_mul_f32 v[46:47], v[46:47], v[102:103]
	s_waitcnt lgkmcnt(2)
	v_pk_mul_f32 v[42:43], v[42:43], v[106:107]
	s_waitcnt lgkmcnt(1)
	v_pk_mul_f32 v[38:39], v[38:39], v[110:111]
	s_waitcnt lgkmcnt(0)
	v_pk_mul_f32 v[34:35], v[34:35], v[114:115]
	v_pk_mul_f32 v[44:45], v[44:45], v[100:101]
	v_pk_mul_f32 v[40:41], v[40:41], v[104:105]
	v_pk_mul_f32 v[36:37], v[36:37], v[108:109]
	v_pk_mul_f32 v[32:33], v[32:33], v[112:113]
	v_pk_mul_f32 v[62:63], v[62:63], v[102:103]
	v_pk_mul_f32 v[58:59], v[58:59], v[106:107]
	v_pk_mul_f32 v[54:55], v[54:55], v[110:111]
	v_pk_mul_f32 v[50:51], v[50:51], v[114:115]
	v_pk_mul_f32 v[60:61], v[60:61], v[100:101]
	v_pk_mul_f32 v[56:57], v[56:57], v[104:105]
	v_pk_mul_f32 v[52:53], v[52:53], v[108:109]
	v_pk_mul_f32 v[48:49], v[48:49], v[112:113]
	v_pk_mul_f32 v[30:31], v[30:31], v[102:103]
	v_pk_mul_f32 v[26:27], v[26:27], v[106:107]
	v_pk_mul_f32 v[22:23], v[22:23], v[110:111]
	v_pk_mul_f32 v[18:19], v[18:19], v[114:115]
	v_pk_mul_f32 v[28:29], v[28:29], v[100:101]
	v_pk_mul_f32 v[24:25], v[24:25], v[104:105]
	v_pk_mul_f32 v[20:21], v[20:21], v[108:109]
	v_pk_mul_f32 v[16:17], v[16:17], v[112:113]
	v_pk_mul_f32 v[14:15], v[14:15], v[102:103]
	v_pk_mul_f32 v[10:11], v[10:11], v[106:107]
	v_pk_mul_f32 v[6:7], v[6:7], v[110:111]
	v_pk_mul_f32 v[2:3], v[2:3], v[114:115]
	v_pk_mul_f32 v[12:13], v[12:13], v[100:101]
	v_pk_mul_f32 v[8:9], v[8:9], v[104:105]
	v_pk_mul_f32 v[4:5], v[4:5], v[108:109]
	v_pk_mul_f32 v[0:1], v[0:1], v[112:113]
.LBB0_221:
	s_waitcnt lgkmcnt(0)
	s_barrier
	ds_read_b128 v[232:235], v197 offset:32768
	ds_read_b128 v[96:99], v197 offset:40960
	ds_read_b128 v[236:239], v217 offset:32768
	ds_read_b128 v[240:243], v217 offset:40960
	v_exp_f32_e32 v85, v85
	v_exp_f32_e32 v86, v86
	v_exp_f32_e32 v87, v87
	s_waitcnt lgkmcnt(3)
	v_mfma_f32_32x32x16_bf16 v[112:127], v[232:235], v[156:159], 0
	ds_read_b128 v[244:247], v218 offset:32768
	v_exp_f32_e32 v88, v88
	v_exp_f32_e32 v89, v89
	v_exp_f32_e32 v90, v90
	v_exp_f32_e32 v91, v91
	v_exp_f32_e32 v92, v92
	s_waitcnt lgkmcnt(3)
	v_mfma_f32_32x32x16_bf16 v[96:111], v[96:99], v[156:159], 0
	ds_read_b128 v[248:251], v218 offset:40960
	v_exp_f32_e32 v83, v95
	v_exp_f32_e32 v95, v176
	v_add_f32_e32 v176, 0, v64
	v_add_f32_e32 v176, v65, v176
	v_add_f32_e32 v176, v66, v176
	s_waitcnt lgkmcnt(3)
	v_mfma_f32_32x32x16_bf16 v[112:127], v[236:239], v[152:155], v[112:127]
	ds_read_b128 v[232:235], v219 offset:32768
	v_add_f32_e32 v176, v67, v176
	v_add_f32_e32 v176, v68, v176
	v_add_f32_e32 v176, v69, v176
	v_add_f32_e32 v176, v70, v176
	v_add_f32_e32 v176, v71, v176
	s_waitcnt lgkmcnt(3)
	v_mfma_f32_32x32x16_bf16 v[96:111], v[240:243], v[152:155], v[96:111]
	ds_read_b128 v[236:239], v219 offset:40960
	v_add_f32_e32 v176, v72, v176
	v_add_f32_e32 v176, v73, v176
	v_add_f32_e32 v176, v74, v176
	v_add_f32_e32 v176, v75, v176
	v_exp_f32_e32 v80, v84
	s_waitcnt lgkmcnt(3)
	v_mfma_f32_32x32x16_bf16 v[112:127], v[244:247], v[148:151], v[112:127]
	ds_read_b128 v[240:243], v197 offset:32896
	v_add_f32_e32 v176, v76, v176
	v_exp_f32_e32 v81, v93
	v_add_f32_e32 v176, v77, v176
	v_exp_f32_e32 v82, v94
	v_add_f32_e32 v176, v78, v176
	s_waitcnt lgkmcnt(3)
	v_mfma_f32_32x32x16_bf16 v[96:111], v[248:251], v[148:151], v[96:111]
	ds_read_b128 v[244:247], v197 offset:41088
	v_add_f32_e32 v176, v79, v176
	v_exp_f32_e32 v84, v177
	v_add_f32_e32 v176, v80, v176
	v_add_f32_e32 v176, v81, v176
	v_add_f32_e32 v176, v82, v176
	s_waitcnt lgkmcnt(3)
	v_mfma_f32_32x32x16_bf16 v[112:127], v[232:235], v[144:147], v[112:127]
	ds_read_b128 v[248:251], v217 offset:32896
	v_add_f32_e32 v176, v83, v176
	v_add_f32_e32 v176, v84, v176
	v_add_f32_e32 v176, v85, v176
	v_add_f32_e32 v176, v86, v176
	v_add_f32_e32 v176, v87, v176
	s_waitcnt lgkmcnt(3)
	v_mfma_f32_32x32x16_bf16 v[96:111], v[236:239], v[144:147], v[96:111]
	ds_read_b128 v[232:235], v217 offset:41088
	v_add_f32_e32 v176, v88, v176
	v_exp_f32_e32 v93, v178
	v_add_f32_e32 v176, v89, v176
	v_exp_f32_e32 v94, v179
	v_add_f32_e32 v176, v90, v176
	s_waitcnt lgkmcnt(3)
	v_mfma_f32_32x32x16_bf16 v[112:127], v[240:243], v[140:143], v[112:127]
	ds_read_b128 v[236:239], v218 offset:32896
	v_add_f32_e32 v176, v91, v176
	v_add_f32_e32 v176, v92, v176
	v_add_f32_e32 v176, v93, v176
	v_add_f32_e32 v176, v94, v176
	v_add_f32_e32 v229, v95, v176
	s_waitcnt lgkmcnt(3)
	v_mfma_f32_32x32x16_bf16 v[96:111], v[244:247], v[140:143], v[96:111]
	ds_read_b128 v[240:243], v218 offset:41088
	v_mov_b32_e32 v230, v229
	v_cvt_pk_bf16_f32 v176, v64, v65
	v_cvt_pk_bf16_f32 v177, v66, v67
	v_cvt_pk_bf16_f32 v178, v68, v69
	v_cvt_pk_bf16_f32 v179, v70, v71
	s_waitcnt lgkmcnt(3)
	v_mfma_f32_32x32x16_bf16 v[112:127], v[248:251], v[136:139], v[112:127]
	ds_read_b128 v[244:247], v219 offset:32896
	v_cvt_pk_bf16_f32 v180, v72, v73
	v_cvt_pk_bf16_f32 v181, v74, v75
	v_cvt_pk_bf16_f32 v182, v76, v77
	v_cvt_pk_bf16_f32 v183, v78, v79
	v_cvt_pk_bf16_f32 v184, v80, v81
	s_waitcnt lgkmcnt(3)
	v_mfma_f32_32x32x16_bf16 v[96:111], v[232:235], v[136:139], v[96:111]
	ds_read_b128 v[248:251], v219 offset:41088
	v_cvt_pk_bf16_f32 v185, v82, v83
	v_cvt_pk_bf16_f32 v186, v84, v85
	v_cvt_pk_bf16_f32 v187, v86, v87
	v_cvt_pk_bf16_f32 v188, v88, v89
	v_cvt_pk_bf16_f32 v189, v90, v91
	s_waitcnt lgkmcnt(3)
	v_mfma_f32_32x32x16_bf16 v[112:127], v[236:239], v[132:135], v[112:127]
	v_cvt_pk_bf16_f32 v190, v92, v93
	v_cvt_pk_bf16_f32 v191, v94, v95
	s_nop 1
	v_permlane32_swap_b32_e32 v229, v230
	v_permlane32_swap_b32_e32 v176, v178
	s_waitcnt lgkmcnt(2)
	v_mfma_f32_32x32x16_bf16 v[96:111], v[240:243], v[132:135], v[96:111]
	v_permlane32_swap_b32_e32 v177, v179
	v_permlane32_swap_b32_e32 v180, v182
	v_permlane32_swap_b32_e32 v181, v183
	v_permlane32_swap_b32_e32 v184, v186
	v_permlane32_swap_b32_e32 v185, v187
	s_waitcnt lgkmcnt(1)
	v_mfma_f32_32x32x16_bf16 v[112:127], v[244:247], v[128:131], v[112:127]
	v_permlane32_swap_b32_e32 v188, v190
	v_permlane32_swap_b32_e32 v189, v191
	s_waitcnt lgkmcnt(0)
	v_mfma_f32_32x32x16_bf16 v[96:111], v[248:251], v[128:131], v[96:111]
	s_add_i32 s3, s86, 1
	s_cmp_lt_u32 s3, s84
	s_cselect_b64 s[72:73], -1, 0
	s_cmp_ge_u32 s3, s84
	s_cbranch_scc1 .LBB0_223
	v_add_u32_e32 v160, 0x41, v228
	v_add_u32_e32 v162, 0x61, v228
	v_ashrrev_i32_e32 v161, 31, v160
	v_ashrrev_i32_e32 v163, 31, v162
	v_lshlrev_b64 v[168:169], 12, v[160:161]
	v_lshlrev_b64 v[170:171], 12, v[162:163]
	v_lshl_add_u64 v[160:161], v[200:201], 0, v[168:169]
	v_lshl_add_u64 v[164:165], v[200:201], 0, v[170:171]
	v_lshl_add_u64 v[168:169], v[202:203], 0, v[168:169]
	v_lshl_add_u64 v[172:173], v[202:203], 0, v[170:171]
	global_load_dwordx4 v[160:163], v[160:161], off
	s_nop 0
	global_load_dwordx4 v[164:167], v[164:165], off
	s_nop 0
	global_load_dwordx4 v[168:171], v[168:169], off
	s_nop 0
	global_load_dwordx4 v[172:175], v[172:173], off
